# P3 tail balance: gMLP half converts the last quarter of the W_down tiles (same code, each tile once) on top of v058
# baseline (speedup 1.0000x reference)
.Lwdn_share:
	s_add_i32 s24, s24, 0x800
	s_branch .LBB0_333

.LBB0_333:
	s_cmpk_gt_i32 s24, 0xfff
	v_mbcnt_lo_u32_b32 v166, -1, 0
	v_mbcnt_hi_u32_b32 v166, -1, v166
	s_cbranch_scc1 .LBB0_340
	v_ashrrev_i32_e32 v1, 3, v166
	v_or_b32_e32 v4, 1, v1
	v_and_b32_e32 v2, -2, v1
	v_ashrrev_i32_e32 v5, 31, v4
	v_lshlrev_b64 v[132:133], 11, v[4:5]
	v_add_u32_e32 v4, 9, v2
	v_ashrrev_i32_e32 v5, 31, v4
	v_ashrrev_i32_e32 v3, 31, v2
	v_lshlrev_b64 v[136:137], 11, v[4:5]
	v_add_u32_e32 v4, 17, v2
	v_lshlrev_b64 v[130:131], 11, v[2:3]
	s_mov_b64 s[0:1], 0x4000
	v_ashrrev_i32_e32 v5, 31, v4
	v_lshl_add_u64 v[134:135], v[130:131], 0, s[0:1]
	s_mov_b64 s[0:1], 0x8000
	v_lshlrev_b64 v[140:141], 11, v[4:5]
	v_add_u32_e32 v4, 25, v2
	v_lshl_add_u64 v[138:139], v[130:131], 0, s[0:1]
	s_mov_b64 s[0:1], 0xc000
	v_ashrrev_i32_e32 v5, 31, v4
	v_lshl_add_u64 v[142:143], v[130:131], 0, s[0:1]
	v_lshlrev_b64 v[144:145], 11, v[4:5]
	s_mov_b64 s[0:1], 0x10000
	v_add_u32_e32 v4, 33, v2
	v_lshl_add_u64 v[146:147], v[130:131], 0, s[0:1]
	v_ashrrev_i32_e32 v5, 31, v4
	s_mov_b64 s[0:1], 0x14000
	v_lshlrev_b64 v[148:149], 11, v[4:5]
	v_lshl_add_u64 v[150:151], v[130:131], 0, s[0:1]
	v_add_u32_e32 v4, 41, v2
	s_mov_b64 s[0:1], 0x18000
	v_lshlrev_b32_e32 v0, 2, v166
	v_ashrrev_i32_e32 v5, 31, v4
	v_lshl_add_u64 v[154:155], v[130:131], 0, s[0:1]
	s_mov_b64 s[0:1], 0x1c000
	v_and_b32_e32 v0, 60, v0
	v_lshlrev_b64 v[152:153], 11, v[4:5]
	v_add_u32_e32 v4, 49, v2
	v_lshl_add_u64 v[158:159], v[130:131], 0, s[0:1]
	v_add_u32_e32 v2, 57, v2
	v_readlane_b32 s0, v254, 3
	v_mov_b32_e32 v129, 0
	v_ashrrev_i32_e32 v5, 31, v4
	v_ashrrev_i32_e32 v3, 31, v2
	s_lshl_b32 s0, s0, 6
	v_readlane_b32 s1, v254, 13
	v_lshlrev_b32_e32 v162, 2, v0
	s_lshl_b32 s8, s57, 3
	v_lshlrev_b64 v[156:157], 11, v[4:5]
	v_lshlrev_b64 v[160:161], 11, v[2:3]
	s_lshl_b32 s9, s57, 4
	s_lshl_b32 s10, s57, 9
	s_lshl_b32 s11, s24, 6
	s_lshl_b32 s12, s57, 10
	v_mov_b32_e32 v164, v162
	v_mov_b32_e32 v165, v129
	s_movk_i32 s13, 0x70
	s_movk_i32 s14, 0x50
	s_movk_i32 s15, 0x60
	s_branch .LBB0_336

.LBB0_336:
	s_add_i32 s16, s8, s24
	s_cmpk_lt_i32 s16, 0xc00
	s_cselect_b64 s[0:1], -1, 0
	s_ashr_i32 s4, s24, 31
	s_lshr_b32 s4, s4, 27
	s_add_i32 s4, s24, s4
	s_ashr_i32 s5, s4, 5
	s_lshl_b32 s4, s5, 6
	s_lshl_b32 s17, s5, 11
	s_ashr_i32 s5, s4, 31
	s_sub_i32 s20, s11, s17
	s_lshl_b64 s[22:23], s[4:5], 13
	s_add_u32 s22, s84, s22
	s_addc_u32 s23, s85, s23
	s_ashr_i32 s21, s20, 31
	s_lshl_b64 s[20:21], s[20:21], 2
	s_add_u32 s20, s22, s20
	s_addc_u32 s21, s23, s21
	v_lshl_add_u64 v[64:65], s[20:21], 0, v[164:165]
	v_lshl_add_u64 v[66:67], v[130:131], 2, v[64:65]
	v_lshl_add_u64 v[68:69], v[132:133], 2, v[64:65]
	global_load_dwordx4 v[120:123], v[66:67], off nt
	global_load_dwordx4 v[124:127], v[68:69], off nt
	v_lshl_add_u64 v[66:67], v[134:135], 2, v[64:65]
	v_lshl_add_u64 v[68:69], v[136:137], 2, v[64:65]
	global_load_dwordx4 v[112:115], v[66:67], off nt
	global_load_dwordx4 v[116:119], v[68:69], off nt
	v_lshl_add_u64 v[66:67], v[138:139], 2, v[64:65]
	v_lshl_add_u64 v[68:69], v[140:141], 2, v[64:65]
	global_load_dwordx4 v[104:107], v[66:67], off nt
	global_load_dwordx4 v[108:111], v[68:69], off nt
	v_lshl_add_u64 v[66:67], v[142:143], 2, v[64:65]
	v_lshl_add_u64 v[68:69], v[144:145], 2, v[64:65]
	global_load_dwordx4 v[96:99], v[66:67], off nt
	global_load_dwordx4 v[100:103], v[68:69], off nt
	v_lshl_add_u64 v[66:67], v[146:147], 2, v[64:65]
	v_lshl_add_u64 v[68:69], v[148:149], 2, v[64:65]
	global_load_dwordx4 v[88:91], v[66:67], off nt
	global_load_dwordx4 v[92:95], v[68:69], off nt
	v_lshl_add_u64 v[66:67], v[150:151], 2, v[64:65]
	v_lshl_add_u64 v[68:69], v[152:153], 2, v[64:65]
	global_load_dwordx4 v[80:83], v[66:67], off nt
	global_load_dwordx4 v[84:87], v[68:69], off nt
	v_lshl_add_u64 v[66:67], v[154:155], 2, v[64:65]
	v_lshl_add_u64 v[68:69], v[156:157], 2, v[64:65]
	global_load_dwordx4 v[72:75], v[66:67], off nt
	global_load_dwordx4 v[76:79], v[68:69], off nt
	v_lshl_add_u64 v[66:67], v[158:159], 2, v[64:65]
	v_lshl_add_u64 v[68:69], v[160:161], 2, v[64:65]
	global_load_dwordx4 v[64:67], v[66:67], off nt
	s_nop 0
	global_load_dwordx4 v[68:71], v[68:69], off nt
	s_cmpk_gt_i32 s16, 0xbff
	s_cbranch_scc1 .LBB0_338
	s_ashr_i32 s20, s16, 31
	s_lshr_b32 s20, s20, 27
	s_add_i32 s20, s16, s20
	s_ashr_i32 s21, s20, 5
	s_lshl_b32 s20, s21, 6
	s_add_i32 s22, s10, s11
	s_lshl_b32 s21, s21, 11
	s_sub_i32 s22, s22, s21
	s_ashr_i32 s21, s20, 31
	s_lshl_b64 s[20:21], s[20:21], 13
	s_add_u32 s42, s84, s20
	s_addc_u32 s43, s85, s21
	s_ashr_i32 s23, s22, 31
	s_lshl_b64 s[20:21], s[22:23], 2
	s_add_u32 s20, s42, s20
	s_addc_u32 s21, s43, s21
	v_mov_b32_e32 v163, v129
	v_lshl_add_u64 v[56:57], s[20:21], 0, v[162:163]
	v_lshl_add_u64 v[0:1], v[130:131], 2, v[56:57]
	v_lshl_add_u64 v[2:3], v[132:133], 2, v[56:57]
	v_lshl_add_u64 v[8:9], v[134:135], 2, v[56:57]
	s_waitcnt lgkmcnt(0)
	v_lshl_add_u64 v[10:11], v[136:137], 2, v[56:57]
	v_lshl_add_u64 v[16:17], v[138:139], 2, v[56:57]
	v_lshl_add_u64 v[18:19], v[140:141], 2, v[56:57]
	v_lshl_add_u64 v[24:25], v[142:143], 2, v[56:57]
	v_lshl_add_u64 v[26:27], v[144:145], 2, v[56:57]
	v_lshl_add_u64 v[32:33], v[146:147], 2, v[56:57]
	v_lshl_add_u64 v[34:35], v[148:149], 2, v[56:57]
	v_lshl_add_u64 v[40:41], v[150:151], 2, v[56:57]
	v_lshl_add_u64 v[42:43], v[152:153], 2, v[56:57]
	v_lshl_add_u64 v[48:49], v[154:155], 2, v[56:57]
	v_lshl_add_u64 v[50:51], v[156:157], 2, v[56:57]
	v_lshl_add_u64 v[58:59], v[158:159], 2, v[56:57]
	v_lshl_add_u64 v[56:57], v[160:161], 2, v[56:57]
	global_load_dwordx4 v[4:7], v[0:1], off nt
	s_nop 0
	global_load_dwordx4 v[0:3], v[2:3], off nt
	s_nop 0
	global_load_dwordx4 v[12:15], v[8:9], off nt
	s_nop 0
	global_load_dwordx4 v[8:11], v[10:11], off nt
	s_nop 0
	global_load_dwordx4 v[20:23], v[16:17], off nt
	s_nop 0
	global_load_dwordx4 v[16:19], v[18:19], off nt
	s_nop 0
	global_load_dwordx4 v[28:31], v[24:25], off nt
	s_nop 0
	global_load_dwordx4 v[24:27], v[26:27], off nt
	s_nop 0
	global_load_dwordx4 v[36:39], v[32:33], off nt
	s_nop 0
	global_load_dwordx4 v[32:35], v[34:35], off nt
	s_nop 0
	global_load_dwordx4 v[44:47], v[40:41], off nt
	s_nop 0
	global_load_dwordx4 v[40:43], v[42:43], off nt
	s_nop 0
	global_load_dwordx4 v[52:55], v[48:49], off nt
	s_nop 0
	global_load_dwordx4 v[48:51], v[50:51], off nt
	s_nop 0
	global_load_dwordx4 v[60:63], v[58:59], off nt
	s_nop 0
	global_load_dwordx4 v[56:59], v[56:57], off nt
